# MLA loop: K/V LDS tiles double-buffered, one barrier per key tile
# speedup vs baseline: 1.0011x; 1.0011x over previous
; template <int DQK>
; DI void attn_tile(const u16* __restrict__ q, int ldq, int qpos0, const Seg& s0, const Seg& s1, int nseg, bool has_sink,
;                   float sinkl2, u16* __restrict__ out, int ldo, char* lds) {
;     ...
;   auto compute = [&](int i) {
;     const Seg& sg = (i < nt0) ? s0 : s1;
;     const int off = ((i < nt0) ? i : i - nt0) << 6;
;     f32x16 sa = zero16(), sb = zero16();
; #pragma unroll
;     for (int ks = 0; ks < NKS; ++ks) {
;       bf16x8 a0 = *(const bf16x8*)(Ks + r * KST + ks * 16 + 8 * h);
;       bf16x8 a1 = *(const bf16x8*)(Ks + (32 + r) * KST + ks * 16 + 8 * h);
;       sa = MFMA(a0, qf[ks], sa);
;       sb = MFMA(a1, qf[ks], sb);
;     }
;     if (sg.masked) {
;       const int qpos = qpos0 + qi;
;       const int kb = sg.pos0 + off;
; #pragma unroll
;       for (int g = 0; g < 16; ++g) {
;         int d0 = kb + crow(g, h) - qpos, d1 = d0 + 32;
;         if (d0 > 128 || d0 < -128) sa[g] = -INFINITY;
;         if (d1 > 128 || d1 < -128) sb[g] = -INFINITY;
;       }
;     }
;     float mx = sa[0];
; #pragma unroll
;     for (int g = 1; g < 16; ++g) mx = fmaxf(mx, sa[g]);
; #pragma unroll
;     for (int g = 0; g < 16; ++g) mx = fmaxf(mx, sb[g]);
;     mx = fmaxf(mx, __shfl_xor(mx, 32));
;     const float mn = fmaxf(m, mx);
;     const float alpha = __builtin_amdgcn_exp2f(m - mn);
;     m = mn;
;     float ps = 0.f;
; #pragma unroll
;     for (int g = 0; g < 16; ++g) { sa[g] = __builtin_amdgcn_exp2f(sa[g] - mn); ps += sa[g]; }
; #pragma unroll
;     for (int g = 0; g < 16; ++g) { sb[g] = __builtin_amdgcn_exp2f(sb[g] - mn); ps += sb[g]; }
;     l = l * alpha + ps;
; #pragma unroll
;     for (int g = 0; g < 16; ++g) { o0[g] *= alpha; o1[g] *= alpha; }
; #pragma unroll
;     for (int kt = 0; kt < 2; ++kt) {
; #pragma unroll
;       for (int s = 0; s < 2; ++s) {
;         const f32x16& sv = kt == 0 ? sa : sb;
;         uint4 pu;
;         pu.x = pack2(sv[8 * s + 0], sv[8 * s + 1]); pu.y = pack2(sv[8 * s + 2], sv[8 * s + 3]);
;         pu.z = pack2(sv[8 * s + 4], sv[8 * s + 5]); pu.w = pack2(sv[8 * s + 6], sv[8 * s + 7]);
;         bf16x8 pf = __builtin_bit_cast(bf16x8, pu);
;         const lds_cptr vp = vp0 + (kt * 32 + 16 * s) * (VST * 2);
;         {
;           s16x4 lo = ATT_VTR(vp);
;           s16x4 hi = ATT_VTR(vp + 8 * VST * 2);
;           bf16x8 vf = __builtin_shufflevector(lo, hi, 0, 1, 2, 3, 4, 5, 6, 7);
.LBB0_602:
	s_add_i32 s22, s22, 2
	s_cmpk_lt_u32 s27, 0x42
	ds_read_b128 v[34:37], v130
	ds_read_b128 v[38:41], v130 offset:6656
	ds_read_b128 v[42:45], v130 offset:32
	s_waitcnt lgkmcnt(2)
	v_mfma_f32_32x32x16_bf16 v[50:65], v[34:37], v[66:69], 0
	ds_read_b128 v[34:37], v130 offset:6688
	v_max3_f32 v137, v184, v185, v186
	v_max3_f32 v137, v137, v187, v188
	v_max3_f32 v137, v137, v189, v190
	v_max3_f32 v137, v137, v191, v192
	s_waitcnt lgkmcnt(2)
	v_mfma_f32_32x32x16_bf16 v[218:233], v[38:41], v[66:69], 0
	ds_read_b128 v[38:41], v130 offset:64
	v_max3_f32 v137, v137, v193, v194
	v_max3_f32 v137, v137, v195, v196
	v_max3_f32 v137, v137, v197, v198
	v_max3_f32 v137, v137, v199, v146
	s_waitcnt lgkmcnt(2)
	v_mfma_f32_32x32x16_bf16 v[50:65], v[42:45], v[70:73], v[50:65]
	ds_read_b128 v[42:45], v130 offset:6720
	v_max3_f32 v137, v137, v147, v148
	v_max3_f32 v137, v137, v149, v150
	v_max3_f32 v137, v137, v151, v152
	v_max3_f32 v137, v137, v153, v154
	s_waitcnt lgkmcnt(2)
	v_mfma_f32_32x32x16_bf16 v[218:233], v[34:37], v[70:73], v[218:233]
	ds_read_b128 v[34:37], v130 offset:96
	v_max3_f32 v137, v137, v155, v156
	v_max3_f32 v137, v137, v157, v158
	v_max3_f32 v137, v137, v159, v160
	v_max3_f32 v137, v137, v161, v161
	s_waitcnt lgkmcnt(2)
	v_mfma_f32_32x32x16_bf16 v[50:65], v[38:41], v[74:77], v[50:65]
	ds_read_b128 v[38:41], v130 offset:6752
	ds_bpermute_b32 v139, v131, v137
	s_waitcnt lgkmcnt(0)
	v_max3_f32 v134, v135, v137, v139
	v_sub_f32_e32 v141, v135, v134
	v_mfma_f32_32x32x16_bf16 v[218:233], v[42:45], v[74:77], v[218:233]
	ds_read_b128 v[42:45], v130 offset:128
	v_exp_f32_e32 v140, v141
	v_mov_b32_e32 v144, v134
	v_mov_b32_e32 v145, v134
	v_sub_f32_e32 v184, v184, v134
	v_mfma_f32_32x32x16_bf16 v[50:65], v[34:37], v[78:81], v[50:65]
	ds_read_b128 v[34:37], v130 offset:6784
	v_sub_f32_e32 v185, v185, v134
	v_sub_f32_e32 v186, v186, v134
	v_sub_f32_e32 v187, v187, v134
	v_sub_f32_e32 v188, v188, v134
	v_mfma_f32_32x32x16_bf16 v[218:233], v[38:41], v[78:81], v[218:233]
	ds_read_b128 v[38:41], v130 offset:160
	v_sub_f32_e32 v189, v189, v134
	v_sub_f32_e32 v190, v190, v134
	v_sub_f32_e32 v191, v191, v134
	v_exp_f32_e32 v184, v184
	s_waitcnt lgkmcnt(2)
	v_mfma_f32_32x32x16_bf16 v[50:65], v[42:45], v[82:85], v[50:65]
	ds_read_b128 v[42:45], v130 offset:6816
	v_sub_f32_e32 v192, v192, v134
	v_sub_f32_e32 v193, v193, v134
	v_sub_f32_e32 v194, v194, v134
	v_sub_f32_e32 v195, v195, v134
	s_waitcnt lgkmcnt(2)
	v_mfma_f32_32x32x16_bf16 v[218:233], v[34:37], v[82:85], v[218:233]
	v_exp_f32_e32 v185, v185
	v_sub_f32_e32 v196, v196, v134
	v_sub_f32_e32 v197, v197, v134
	v_sub_f32_e32 v198, v198, v134
	s_waitcnt lgkmcnt(1)
	v_mfma_f32_32x32x16_bf16 v[50:65], v[38:41], v[86:89], v[50:65]
	v_sub_f32_e32 v199, v199, v134
	v_exp_f32_e32 v186, v186
	v_sub_f32_e32 v146, v146, v134
	v_sub_f32_e32 v147, v147, v134
	s_waitcnt lgkmcnt(0)
	v_mfma_f32_32x32x16_bf16 v[218:233], v[42:45], v[86:89], v[218:233]
	ds_read_b64_tr_b16 v[46:47], v133 offset:46080
	ds_read_b64_tr_b16 v[48:49], v133 offset:47616
	ds_read_b64_tr_b16 v[200:201], v133 offset:46144
	ds_read_b64_tr_b16 v[202:203], v133 offset:47680
	ds_read_b64_tr_b16 v[204:205], v133 offset:49152
	ds_read_b64_tr_b16 v[206:207], v133 offset:50688
	ds_read_b64_tr_b16 v[234:235], v133 offset:49216
	ds_read_b64_tr_b16 v[236:237], v133 offset:50752
	v_sub_f32_e32 v148, v148, v134
	v_sub_f32_e32 v149, v149, v134
	v_exp_f32_e32 v187, v187
	v_sub_f32_e32 v150, v150, v134
	v_sub_f32_e32 v151, v151, v134
	v_sub_f32_e32 v152, v152, v134
	v_sub_f32_e32 v153, v153, v134
	v_exp_f32_e32 v188, v188
	v_mul_f32_e32 v33, v140, v33
	v_mul_f32_e32 v32, v140, v32
	v_mul_f32_e32 v31, v140, v31
	v_mul_f32_e32 v30, v140, v30
	v_exp_f32_e32 v189, v189
	v_mul_f32_e32 v29, v140, v29
	v_mul_f32_e32 v28, v140, v28
	v_mul_f32_e32 v27, v140, v27
	v_mul_f32_e32 v26, v140, v26
	v_exp_f32_e32 v190, v190
	v_mul_f32_e32 v25, v140, v25
	v_mul_f32_e32 v24, v140, v24
	v_mul_f32_e32 v23, v140, v23
	v_mul_f32_e32 v22, v140, v22
	v_exp_f32_e32 v191, v191
	v_mul_f32_e32 v21, v140, v21
	v_mul_f32_e32 v20, v140, v20
	v_mul_f32_e32 v19, v140, v19
	v_mul_f32_e32 v18, v140, v18
	v_exp_f32_e32 v192, v192
	v_sub_f32_e32 v154, v154, v134
	v_sub_f32_e32 v155, v155, v134
	v_sub_f32_e32 v156, v156, v134
	v_sub_f32_e32 v157, v157, v134
	v_sub_f32_e32 v158, v158, v134
	v_exp_f32_e32 v193, v193
	v_sub_f32_e32 v159, v159, v134
	v_sub_f32_e32 v160, v160, v134
	v_sub_f32_e32 v161, v161, v134
	v_mul_f32_e32 v17, v140, v17
	v_mul_f32_e32 v16, v140, v16
	v_exp_f32_e32 v194, v194
	v_mul_f32_e32 v15, v140, v15
	v_mul_f32_e32 v14, v140, v14
	v_mul_f32_e32 v13, v140, v13
	v_mul_f32_e32 v12, v140, v12
	v_mul_f32_e32 v11, v140, v11
	v_exp_f32_e32 v195, v195
	v_mul_f32_e32 v10, v140, v10
	v_mul_f32_e32 v9, v140, v9
	v_mul_f32_e32 v8, v140, v8
	v_mul_f32_e32 v7, v140, v7
	v_mul_f32_e32 v6, v140, v6
	v_exp_f32_e32 v196, v196
	v_mul_f32_e32 v5, v140, v5
	v_mul_f32_e32 v4, v140, v4
	v_mul_f32_e32 v3, v140, v3
	v_mul_f32_e32 v2, v140, v2
	v_add_f32_e32 v238, v184, v185
	v_exp_f32_e32 v197, v197
	v_add_f32_e32 v238, v238, v186
	v_add_f32_e32 v238, v238, v187
	v_add_f32_e32 v238, v238, v188
	v_add_f32_e32 v238, v238, v189
	v_add_f32_e32 v238, v238, v190
	v_exp_f32_e32 v198, v198
	v_add_f32_e32 v238, v238, v191
	v_cvt_pk_bf16_f32 v184, v184, v185
	v_cvt_pk_bf16_f32 v185, v186, v187
	v_cvt_pk_bf16_f32 v186, v188, v189
	v_cvt_pk_bf16_f32 v187, v190, v191
	v_exp_f32_e32 v199, v199
	s_nop 0
	s_waitcnt lgkmcnt(6)
; #define MFMA(a, b, c) __builtin_amdgcn_mfma_f32_32x32x16_bf16((a), (b), (c), 0, 0, 0)
; #define ATT_VTR(p) __builtin_bit_cast(s16x4, __builtin_amdgcn_ds_read_tr16_b64_v4i16((__attribute__((address_space(3))) v4i16_t*)(p)))
; template <int DQK>
; DI void attn_tile(const u16* __restrict__ q, int ldq, int qpos0, const Seg& s0, const Seg& s1, int nseg, bool has_sink,
;                   float sinkl2, u16* __restrict__ out, int ldo, char* lds) {
;     ...
; #pragma unroll
;     for (int kt = 0; kt < 2; ++kt) {
; #pragma unroll
;       for (int s = 0; s < 2; ++s) {
;         const f32x16& sv = kt == 0 ? sa : sb;
;         uint4 pu;
;         pu.x = pack2(sv[8 * s + 0], sv[8 * s + 1]); pu.y = pack2(sv[8 * s + 2], sv[8 * s + 3]);
;         pu.z = pack2(sv[8 * s + 4], sv[8 * s + 5]); pu.w = pack2(sv[8 * s + 6], sv[8 * s + 7]);
;         bf16x8 pf = __builtin_bit_cast(bf16x8, pu);
;         const lds_cptr vp = vp0 + (kt * 32 + 16 * s) * (VST * 2);
;         {
;           s16x4 lo = ATT_VTR(vp);
;           s16x4 hi = ATT_VTR(vp + 8 * VST * 2);
;           bf16x8 vf = __builtin_shufflevector(lo, hi, 0, 1, 2, 3, 4, 5, 6, 7);
;           o0 = MFMA(vf, pf, o0);
;         }
;         {
;           s16x4 lo = ATT_VTR(vp + 64);
;           s16x4 hi = ATT_VTR(vp + 8 * VST * 2 + 64);
;           bf16x8 vf = __builtin_shufflevector(lo, hi, 0, 1, 2, 3, 4, 5, 6, 7);
;           o1 = MFMA(vf, pf, o1);
;         }
;       }
;     }
;   };
;   ATT_LOADX(0, kreg0, kreg1, vreg0);
;   ATT_LOADX(1, krgB0, krgB1, vrgB0);
;   for (int i = 0; i < NT; i += 2) {
;     __syncthreads();
;     ATT_STOREX(kreg0, kreg1, vreg0);
;     __syncthreads();
;     if (i + 2 < NT) ATT_LOADX(i + 2, kreg0, kreg1, vreg0);
;     compute(i);
;     __syncthreads();
;     ATT_STOREX(krgB0, krgB1, vrgB0);
;     __syncthreads();
;     if (i + 3 < NT) ATT_LOADX(i + 3, krgB0, krgB1, vrgB0);
;     compute(i + 1);
	v_mfma_f32_32x32x16_bf16 v[18:33], v[46:49], v[184:187], v[18:33]
	ds_read_b64_tr_b16 v[46:47], v133 offset:52224
	ds_read_b64_tr_b16 v[48:49], v133 offset:53760
	s_waitcnt lgkmcnt(6)
	v_mfma_f32_32x32x16_bf16 v[2:17], v[200:203], v[184:187], v[2:17]
	ds_read_b64_tr_b16 v[200:201], v133 offset:52288
	ds_read_b64_tr_b16 v[202:203], v133 offset:53824
	v_exp_f32_e32 v146, v146
	v_add_f32_e32 v238, v238, v192
	v_add_f32_e32 v238, v238, v193
	v_exp_f32_e32 v147, v147
	v_add_f32_e32 v238, v238, v194
	v_add_f32_e32 v238, v238, v195
	v_exp_f32_e32 v148, v148
	v_add_f32_e32 v238, v238, v196
	v_add_f32_e32 v238, v238, v197
	v_exp_f32_e32 v149, v149
	v_add_f32_e32 v238, v238, v198
	v_add_f32_e32 v238, v238, v199
	v_exp_f32_e32 v150, v150
	v_cvt_pk_bf16_f32 v188, v192, v193
	v_cvt_pk_bf16_f32 v189, v194, v195
	v_exp_f32_e32 v151, v151
	v_cvt_pk_bf16_f32 v190, v196, v197
	v_cvt_pk_bf16_f32 v191, v198, v199
	v_exp_f32_e32 v152, v152
	v_exp_f32_e32 v153, v153
	s_nop 0
	s_waitcnt lgkmcnt(6)
	v_mfma_f32_32x32x16_bf16 v[18:33], v[204:207], v[188:191], v[18:33]
	ds_read_b64_tr_b16 v[204:205], v133 offset:55296
	ds_read_b64_tr_b16 v[206:207], v133 offset:56832
	s_waitcnt lgkmcnt(6)
	v_mfma_f32_32x32x16_bf16 v[2:17], v[234:237], v[188:191], v[2:17]
	ds_read_b64_tr_b16 v[234:235], v133 offset:55360
	ds_read_b64_tr_b16 v[236:237], v133 offset:56896
	v_exp_f32_e32 v154, v154
	v_add_f32_e32 v238, v238, v146
	v_add_f32_e32 v238, v238, v147
	v_exp_f32_e32 v155, v155
	v_add_f32_e32 v238, v238, v148
	v_add_f32_e32 v238, v238, v149
	v_exp_f32_e32 v156, v156
	v_add_f32_e32 v238, v238, v150
	v_add_f32_e32 v238, v238, v151
	v_exp_f32_e32 v157, v157
	v_add_f32_e32 v238, v238, v152
	v_add_f32_e32 v238, v238, v153
	v_exp_f32_e32 v158, v158
	v_cvt_pk_bf16_f32 v146, v146, v147
	v_cvt_pk_bf16_f32 v147, v148, v149
	v_exp_f32_e32 v159, v159
	v_cvt_pk_bf16_f32 v148, v150, v151
	v_cvt_pk_bf16_f32 v149, v152, v153
	v_exp_f32_e32 v160, v160
	v_exp_f32_e32 v161, v161
	s_nop 0
	s_waitcnt lgkmcnt(6)
	v_mfma_f32_32x32x16_bf16 v[18:33], v[46:49], v[146:149], v[18:33]
	s_waitcnt lgkmcnt(4)
	v_mfma_f32_32x32x16_bf16 v[2:17], v[200:203], v[146:149], v[2:17]
	v_add_f32_e32 v238, v238, v154
	v_add_f32_e32 v238, v238, v155
	v_add_f32_e32 v238, v238, v156
	v_add_f32_e32 v238, v238, v157
	v_add_f32_e32 v238, v238, v158
	v_add_f32_e32 v238, v238, v159
	v_add_f32_e32 v238, v238, v160
	v_add_f32_e32 v238, v238, v161
	v_cvt_pk_bf16_f32 v150, v154, v155
	v_cvt_pk_bf16_f32 v151, v156, v157
	v_cvt_pk_bf16_f32 v152, v158, v159
	v_cvt_pk_bf16_f32 v153, v160, v161
	s_nop 0
	s_waitcnt lgkmcnt(2)
	v_mfma_f32_32x32x16_bf16 v[18:33], v[204:207], v[150:153], v[18:33]
	s_waitcnt lgkmcnt(0)
	v_mfma_f32_32x32x16_bf16 v[2:17], v[234:237], v[150:153], v[2:17]
	v_fma_f32 v128, v136, v140, v238
	s_cbranch_scc0 .LBB0_727
.LBB0_603:
	s_nop 0
	s_waitcnt vmcnt(0)
	ds_write_b128 v121, v[98:101] offset:32768
	s_and_saveexec_b64 s[4:5], s[0:1]
	ds_write_b128 v129, v[106:109] offset:32768
	s_or_b64 exec, exec, s[4:5]
	s_add_i32 s27, s22, -3
	s_cmpk_gt_u32 s27, 0x41
	s_waitcnt vmcnt(2)
	ds_write_b128 v132, v[102:105] offset:13312
	s_waitcnt lgkmcnt(0)
	s_barrier
	s_cbranch_scc1 .LBB0_617
	s_cmp_lt_u32 s27, 62
	s_cselect_b64 s[4:5], -1, 0
	s_and_b64 s[16:17], s[4:5], exec
	s_cselect_b32 s16, 0, 0x3ffffc0
	s_add_i32 s16, s16, s22
	s_lshl_b32 s16, s16, 6
	s_sub_i32 s28, s16, 64
	v_add_u32_e32 v34, s28, v116
	v_ashrrev_i32_e32 v35, 31, v34
	s_and_saveexec_b64 s[16:17], vcc
	s_xor_b64 s[16:17], exec, s[16:17]
	s_cbranch_execz .LBB0_609
	s_and_b64 s[18:19], s[4:5], exec
	s_cselect_b32 s19, s15, s11
	s_cselect_b32 s18, s14, s10
	v_lshlrev_b64 v[34:35], 6, v[34:35]
	v_lshl_add_u64 v[34:35], s[18:19], 0, v[34:35]
	s_movk_i32 s18, 0xff80
	v_lshl_add_u64 v[34:35], v[124:125], 1, v[34:35]
	s_mov_b32 s19, -1
	v_lshl_add_u64 v[36:37], v[34:35], 0, s[18:19]
	s_andn2_saveexec_b64 s[16:17], s[16:17]
	s_cbranch_execnz .LBB0_610

; #define MFMA(a, b, c) __builtin_amdgcn_mfma_f32_32x32x16_bf16((a), (b), (c), 0, 0, 0)
; DI int crow(int reg, int h) { return (reg & 3) + 8 * (reg >> 2) + 4 * h; }
; template <int DQK>
; DI void attn_tile(const u16* __restrict__ q, int ldq, int qpos0, const Seg& s0, const Seg& s1, int nseg, bool has_sink,
;                   float sinkl2, u16* __restrict__ out, int ldo, char* lds) {
;     ...
;   auto compute = [&](int i) {
;     const Seg& sg = (i < nt0) ? s0 : s1;
;     const int off = ((i < nt0) ? i : i - nt0) << 6;
;     f32x16 sa = zero16(), sb = zero16();
; #pragma unroll
;     for (int ks = 0; ks < NKS; ++ks) {
;       bf16x8 a0 = *(const bf16x8*)(Ks + r * KST + ks * 16 + 8 * h);
;       bf16x8 a1 = *(const bf16x8*)(Ks + (32 + r) * KST + ks * 16 + 8 * h);
;       sa = MFMA(a0, qf[ks], sa);
;       sb = MFMA(a1, qf[ks], sb);
;     }
;     if (sg.masked) {
;       const int qpos = qpos0 + qi;
;       const int kb = sg.pos0 + off;
; #pragma unroll
;       for (int g = 0; g < 16; ++g) {
;         int d0 = kb + crow(g, h) - qpos, d1 = d0 + 32;
;         if (d0 > 128 || d0 < -128) sa[g] = -INFINITY;
;         if (d1 > 128 || d1 < -128) sb[g] = -INFINITY;
;       }
;     }
;     float mx = sa[0];
; #pragma unroll
;     for (int g = 1; g < 16; ++g) mx = fmaxf(mx, sa[g]);
; #pragma unroll
;     for (int g = 0; g < 16; ++g) mx = fmaxf(mx, sb[g]);
;     mx = fmaxf(mx, __shfl_xor(mx, 32));
;     const float mn = fmaxf(m, mx);
;     const float alpha = __builtin_amdgcn_exp2f(m - mn);
;     m = mn;
;     float ps = 0.f;
; #pragma unroll
;     for (int g = 0; g < 16; ++g) { sa[g] = __builtin_amdgcn_exp2f(sa[g] - mn); ps += sa[g]; }
; #pragma unroll
;     for (int g = 0; g < 16; ++g) { sb[g] = __builtin_amdgcn_exp2f(sb[g] - mn); ps += sb[g]; }
;     l = l * alpha + ps;
; #pragma unroll
;     for (int g = 0; g < 16; ++g) { o0[g] *= alpha; o1[g] *= alpha; }
.LBB0_617:
	ds_read_b128 v[34:37], v130 offset:32768
	ds_read_b128 v[38:41], v130 offset:39424
	ds_read_b128 v[42:45], v130 offset:32800
	s_waitcnt lgkmcnt(2)
	v_mfma_f32_32x32x16_bf16 v[184:199], v[34:37], v[66:69], 0
	ds_read_b128 v[34:37], v130 offset:39456
	v_max3_f32 v137, v50, v51, v52
	v_max3_f32 v137, v137, v53, v54
	v_max3_f32 v137, v137, v55, v56
	v_max3_f32 v137, v137, v57, v58
	s_waitcnt lgkmcnt(2)
	v_mfma_f32_32x32x16_bf16 v[146:161], v[38:41], v[66:69], 0
	ds_read_b128 v[38:41], v130 offset:32832
	v_max3_f32 v137, v137, v59, v60
	v_max3_f32 v137, v137, v61, v62
	v_max3_f32 v137, v137, v63, v64
	v_max3_f32 v137, v137, v65, v218
	s_waitcnt lgkmcnt(2)
	v_mfma_f32_32x32x16_bf16 v[184:199], v[42:45], v[70:73], v[184:199]
	ds_read_b128 v[42:45], v130 offset:39488
	v_max3_f32 v137, v137, v219, v220
	v_max3_f32 v137, v137, v221, v222
	v_max3_f32 v137, v137, v223, v224
	v_max3_f32 v137, v137, v225, v226
	s_waitcnt lgkmcnt(2)
	v_mfma_f32_32x32x16_bf16 v[146:161], v[34:37], v[70:73], v[146:161]
	ds_read_b128 v[34:37], v130 offset:32864
	v_max3_f32 v137, v137, v227, v228
	v_max3_f32 v137, v137, v229, v230
	v_max3_f32 v137, v137, v231, v232
	v_max3_f32 v137, v137, v233, v233
	s_waitcnt lgkmcnt(2)
	v_mfma_f32_32x32x16_bf16 v[184:199], v[38:41], v[74:77], v[184:199]
	ds_read_b128 v[38:41], v130 offset:39520
	ds_bpermute_b32 v139, v131, v137
	s_waitcnt lgkmcnt(0)
	v_max3_f32 v135, v134, v137, v139
	v_sub_f32_e32 v141, v134, v135
	v_mfma_f32_32x32x16_bf16 v[146:161], v[42:45], v[74:77], v[146:161]
	ds_read_b128 v[42:45], v130 offset:32896
	v_exp_f32_e32 v140, v141
	v_mov_b32_e32 v144, v135
	v_mov_b32_e32 v145, v135
	v_sub_f32_e32 v50, v50, v135
	v_mfma_f32_32x32x16_bf16 v[184:199], v[34:37], v[78:81], v[184:199]
	ds_read_b128 v[34:37], v130 offset:39552
	v_sub_f32_e32 v51, v51, v135
	v_sub_f32_e32 v52, v52, v135
	v_sub_f32_e32 v53, v53, v135
	v_sub_f32_e32 v54, v54, v135
	v_mfma_f32_32x32x16_bf16 v[146:161], v[38:41], v[78:81], v[146:161]
	ds_read_b128 v[38:41], v130 offset:32928
	v_sub_f32_e32 v55, v55, v135
	v_sub_f32_e32 v56, v56, v135
	v_sub_f32_e32 v57, v57, v135
	v_exp_f32_e32 v50, v50
	s_waitcnt lgkmcnt(2)
	v_mfma_f32_32x32x16_bf16 v[184:199], v[42:45], v[82:85], v[184:199]
	ds_read_b128 v[42:45], v130 offset:39584
	v_sub_f32_e32 v58, v58, v135
	v_sub_f32_e32 v59, v59, v135
	v_sub_f32_e32 v60, v60, v135
	v_sub_f32_e32 v61, v61, v135
	s_waitcnt lgkmcnt(2)
	v_mfma_f32_32x32x16_bf16 v[146:161], v[34:37], v[82:85], v[146:161]
	v_exp_f32_e32 v51, v51
	v_sub_f32_e32 v62, v62, v135
	v_sub_f32_e32 v63, v63, v135
	v_sub_f32_e32 v64, v64, v135
	s_waitcnt lgkmcnt(1)
	v_mfma_f32_32x32x16_bf16 v[184:199], v[38:41], v[86:89], v[184:199]
	v_sub_f32_e32 v65, v65, v135
	v_exp_f32_e32 v52, v52
	v_sub_f32_e32 v218, v218, v135
	v_sub_f32_e32 v219, v219, v135
	s_waitcnt lgkmcnt(0)
	v_mfma_f32_32x32x16_bf16 v[146:161], v[42:45], v[86:89], v[146:161]
	ds_read_b64_tr_b16 v[46:47], v133 offset:13312
	ds_read_b64_tr_b16 v[48:49], v133 offset:14848
	ds_read_b64_tr_b16 v[200:201], v133 offset:13376
	ds_read_b64_tr_b16 v[202:203], v133 offset:14912
	ds_read_b64_tr_b16 v[204:205], v133 offset:16384
	ds_read_b64_tr_b16 v[206:207], v133 offset:17920
	ds_read_b64_tr_b16 v[234:235], v133 offset:16448
	ds_read_b64_tr_b16 v[236:237], v133 offset:17984
	v_sub_f32_e32 v220, v220, v135
	v_sub_f32_e32 v221, v221, v135
	v_exp_f32_e32 v53, v53
	v_sub_f32_e32 v222, v222, v135
	v_sub_f32_e32 v223, v223, v135
	v_sub_f32_e32 v224, v224, v135
	v_sub_f32_e32 v225, v225, v135
	v_exp_f32_e32 v54, v54
	v_mul_f32_e32 v33, v140, v33
	v_mul_f32_e32 v32, v140, v32
	v_mul_f32_e32 v31, v140, v31
	v_mul_f32_e32 v30, v140, v30
	v_exp_f32_e32 v55, v55
	v_mul_f32_e32 v29, v140, v29
	v_mul_f32_e32 v28, v140, v28
	v_mul_f32_e32 v27, v140, v27
	v_mul_f32_e32 v26, v140, v26
	v_exp_f32_e32 v56, v56
	v_mul_f32_e32 v25, v140, v25
	v_mul_f32_e32 v24, v140, v24
	v_mul_f32_e32 v23, v140, v23
	v_mul_f32_e32 v22, v140, v22
	v_exp_f32_e32 v57, v57
	v_mul_f32_e32 v21, v140, v21
	v_mul_f32_e32 v20, v140, v20
	v_mul_f32_e32 v19, v140, v19
	v_mul_f32_e32 v18, v140, v18
	v_exp_f32_e32 v58, v58
	v_sub_f32_e32 v226, v226, v135
	v_sub_f32_e32 v227, v227, v135
	v_sub_f32_e32 v228, v228, v135
	v_sub_f32_e32 v229, v229, v135
	v_sub_f32_e32 v230, v230, v135
	v_exp_f32_e32 v59, v59
	v_sub_f32_e32 v231, v231, v135
	v_sub_f32_e32 v232, v232, v135
	v_sub_f32_e32 v233, v233, v135
	v_mul_f32_e32 v17, v140, v17
	v_mul_f32_e32 v16, v140, v16
	v_exp_f32_e32 v60, v60
	v_mul_f32_e32 v15, v140, v15
	v_mul_f32_e32 v14, v140, v14
	v_mul_f32_e32 v13, v140, v13
	v_mul_f32_e32 v12, v140, v12
	v_mul_f32_e32 v11, v140, v11
	v_exp_f32_e32 v61, v61
	v_mul_f32_e32 v10, v140, v10
	v_mul_f32_e32 v9, v140, v9
	v_mul_f32_e32 v8, v140, v8
	v_mul_f32_e32 v7, v140, v7
	v_mul_f32_e32 v6, v140, v6
	v_exp_f32_e32 v62, v62
	v_mul_f32_e32 v5, v140, v5
	v_mul_f32_e32 v4, v140, v4
	v_mul_f32_e32 v3, v140, v3
	v_mul_f32_e32 v2, v140, v2
	v_add_f32_e32 v238, v50, v51
	v_exp_f32_e32 v63, v63
	v_add_f32_e32 v238, v238, v52
	v_add_f32_e32 v238, v238, v53
	v_add_f32_e32 v238, v238, v54
	v_add_f32_e32 v238, v238, v55
	v_add_f32_e32 v238, v238, v56
	v_exp_f32_e32 v64, v64
	v_add_f32_e32 v238, v238, v57
	v_cvt_pk_bf16_f32 v50, v50, v51
	v_cvt_pk_bf16_f32 v51, v52, v53
	v_cvt_pk_bf16_f32 v52, v54, v55
	v_cvt_pk_bf16_f32 v53, v56, v57
	v_exp_f32_e32 v65, v65
	s_nop 0
	s_waitcnt lgkmcnt(6)
; #define MFMA(a, b, c) __builtin_amdgcn_mfma_f32_32x32x16_bf16((a), (b), (c), 0, 0, 0)
; #define ATT_VTR(p) __builtin_bit_cast(s16x4, __builtin_amdgcn_ds_read_tr16_b64_v4i16((__attribute__((address_space(3))) v4i16_t*)(p)))
; template <int DQK>
; DI void attn_tile(const u16* __restrict__ q, int ldq, int qpos0, const Seg& s0, const Seg& s1, int nseg, bool has_sink,
;                   float sinkl2, u16* __restrict__ out, int ldo, char* lds) {
;     ...
; #pragma unroll
;     for (int kt = 0; kt < 2; ++kt) {
; #pragma unroll
;       for (int s = 0; s < 2; ++s) {
;         const f32x16& sv = kt == 0 ? sa : sb;
;         uint4 pu;
;         pu.x = pack2(sv[8 * s + 0], sv[8 * s + 1]); pu.y = pack2(sv[8 * s + 2], sv[8 * s + 3]);
;         pu.z = pack2(sv[8 * s + 4], sv[8 * s + 5]); pu.w = pack2(sv[8 * s + 6], sv[8 * s + 7]);
;         bf16x8 pf = __builtin_bit_cast(bf16x8, pu);
;         const lds_cptr vp = vp0 + (kt * 32 + 16 * s) * (VST * 2);
;         {
;           s16x4 lo = ATT_VTR(vp);
;           s16x4 hi = ATT_VTR(vp + 8 * VST * 2);
;           bf16x8 vf = __builtin_shufflevector(lo, hi, 0, 1, 2, 3, 4, 5, 6, 7);
;           o0 = MFMA(vf, pf, o0);
;         }
;         {
;           s16x4 lo = ATT_VTR(vp + 64);
;           s16x4 hi = ATT_VTR(vp + 8 * VST * 2 + 64);
;           bf16x8 vf = __builtin_shufflevector(lo, hi, 0, 1, 2, 3, 4, 5, 6, 7);
;           o1 = MFMA(vf, pf, o1);
;         }
;       }
;     }
;   };
;   ATT_LOADX(0, kreg0, kreg1, vreg0);
;   ATT_LOADX(1, krgB0, krgB1, vrgB0);
;   for (int i = 0; i < NT; i += 2) {
;     __syncthreads();
;     ATT_STOREX(kreg0, kreg1, vreg0);
;     __syncthreads();
;     if (i + 2 < NT) ATT_LOADX(i + 2, kreg0, kreg1, vreg0);
;     compute(i);
;     __syncthreads();
;     ATT_STOREX(krgB0, krgB1, vrgB0);
;     __syncthreads();
;     if (i + 3 < NT) ATT_LOADX(i + 3, krgB0, krgB1, vrgB0);
;     compute(i + 1);
	v_mfma_f32_32x32x16_bf16 v[18:33], v[46:49], v[50:53], v[18:33]
	ds_read_b64_tr_b16 v[46:47], v133 offset:19456
	ds_read_b64_tr_b16 v[48:49], v133 offset:20992
	s_waitcnt lgkmcnt(6)
	v_mfma_f32_32x32x16_bf16 v[2:17], v[200:203], v[50:53], v[2:17]
	ds_read_b64_tr_b16 v[200:201], v133 offset:19520
	ds_read_b64_tr_b16 v[202:203], v133 offset:21056
	v_exp_f32_e32 v218, v218
	v_add_f32_e32 v238, v238, v58
	v_add_f32_e32 v238, v238, v59
	v_exp_f32_e32 v219, v219
	v_add_f32_e32 v238, v238, v60
	v_add_f32_e32 v238, v238, v61
	v_exp_f32_e32 v220, v220
	v_add_f32_e32 v238, v238, v62
	v_add_f32_e32 v238, v238, v63
	v_exp_f32_e32 v221, v221
	v_add_f32_e32 v238, v238, v64
	v_add_f32_e32 v238, v238, v65
	v_exp_f32_e32 v222, v222
	v_cvt_pk_bf16_f32 v54, v58, v59
	v_cvt_pk_bf16_f32 v55, v60, v61
	v_exp_f32_e32 v223, v223
	v_cvt_pk_bf16_f32 v56, v62, v63
	v_cvt_pk_bf16_f32 v57, v64, v65
	v_exp_f32_e32 v224, v224
	v_exp_f32_e32 v225, v225
	s_nop 0
	s_waitcnt lgkmcnt(6)
	v_mfma_f32_32x32x16_bf16 v[18:33], v[204:207], v[54:57], v[18:33]
	ds_read_b64_tr_b16 v[204:205], v133 offset:22528
	ds_read_b64_tr_b16 v[206:207], v133 offset:24064
	s_waitcnt lgkmcnt(6)
	v_mfma_f32_32x32x16_bf16 v[2:17], v[234:237], v[54:57], v[2:17]
	ds_read_b64_tr_b16 v[234:235], v133 offset:22592
	ds_read_b64_tr_b16 v[236:237], v133 offset:24128
	v_exp_f32_e32 v226, v226
	v_add_f32_e32 v238, v238, v218
	v_add_f32_e32 v238, v238, v219
	v_exp_f32_e32 v227, v227
	v_add_f32_e32 v238, v238, v220
	v_add_f32_e32 v238, v238, v221
	v_exp_f32_e32 v228, v228
	v_add_f32_e32 v238, v238, v222
	v_add_f32_e32 v238, v238, v223
	v_exp_f32_e32 v229, v229
	v_add_f32_e32 v238, v238, v224
	v_add_f32_e32 v238, v238, v225
	v_exp_f32_e32 v230, v230
	v_cvt_pk_bf16_f32 v218, v218, v219
	v_cvt_pk_bf16_f32 v219, v220, v221
	v_exp_f32_e32 v231, v231
	v_cvt_pk_bf16_f32 v220, v222, v223
	v_cvt_pk_bf16_f32 v221, v224, v225
	v_exp_f32_e32 v232, v232
	v_exp_f32_e32 v233, v233
	s_nop 0
	s_waitcnt lgkmcnt(6)
	v_mfma_f32_32x32x16_bf16 v[18:33], v[46:49], v[218:221], v[18:33]
	s_waitcnt lgkmcnt(4)
	v_mfma_f32_32x32x16_bf16 v[2:17], v[200:203], v[218:221], v[2:17]
	v_add_f32_e32 v238, v238, v226
	v_add_f32_e32 v238, v238, v227
	v_add_f32_e32 v238, v238, v228
	v_add_f32_e32 v238, v238, v229
	v_add_f32_e32 v238, v238, v230
	v_add_f32_e32 v238, v238, v231
	v_add_f32_e32 v238, v238, v232
	v_add_f32_e32 v238, v238, v233
	v_cvt_pk_bf16_f32 v222, v226, v227
	v_cvt_pk_bf16_f32 v223, v228, v229
	v_cvt_pk_bf16_f32 v224, v230, v231
	v_cvt_pk_bf16_f32 v225, v232, v233
	s_nop 0
	s_waitcnt lgkmcnt(2)
	v_mfma_f32_32x32x16_bf16 v[18:33], v[204:207], v[222:225], v[18:33]
	s_waitcnt lgkmcnt(0)
	v_mfma_f32_32x32x16_bf16 v[2:17], v[234:237], v[222:225], v[2:17]
	v_fma_f32 v136, v128, v140, v238
	s_waitcnt vmcnt(0)
	ds_write_b128 v121, v[90:93]
	s_and_saveexec_b64 s[4:5], s[0:1]
	ds_write_b128 v129, v[94:97]
	s_or_b64 exec, exec, s[4:5]
	s_cmp_gt_u32 s27, 64
	ds_write_b128 v132, v[110:113] offset:46080
	s_waitcnt lgkmcnt(0)
	s_barrier
	s_cbranch_scc1 .LBB0_602
	s_cmp_lt_u32 s27, 61
	s_cselect_b64 s[4:5], -1, 0
	s_and_b64 s[16:17], s[4:5], exec
	s_cselect_b32 s16, 0, 0x3ffffc0
	s_add_i32 s16, s16, s22
	s_lshl_b32 s28, s16, 6
	v_add_u32_e32 v36, s28, v116
	v_ashrrev_i32_e32 v37, 31, v36
	s_and_saveexec_b64 s[16:17], vcc
	s_xor_b64 s[16:17], exec, s[16:17]
	s_cbranch_execz .LBB0_623
	s_and_b64 s[18:19], s[4:5], exec
	s_cselect_b32 s19, s15, s11
	s_cselect_b32 s18, s14, s10
	v_lshlrev_b64 v[36:37], 6, v[36:37]
	v_lshl_add_u64 v[36:37], s[18:19], 0, v[36:37]
	s_movk_i32 s18, 0xff80
	v_lshl_add_u64 v[36:37], v[124:125], 1, v[36:37]
	s_mov_b32 s19, -1
	v_lshl_add_u64 v[38:39], v[36:37], 0, s[18:19]
	s_andn2_saveexec_b64 s[16:17], s[16:17]
	s_cbranch_execnz .LBB0_624
